# P7: half the WGs run the down-GEMM units first and their 64x64 sample-row tile last (LDS-bound small tiles overlap the other half's GEMM)
# baseline (speedup 1.0000x reference)
; __global__ void __launch_bounds__(512, 2) hybrid_fwd(Args a) {
;     ...
;     if (IN(7)) {
;         for (int t = bx; t < 256; t += G) { SmResidB<1> E{nullptr, X1B, Y, SSF}; small_gemm_tile<SmResidB<1>>(lds, HID, DFF, WDN, DFF, DFF, -1, MP, t >> 5, t & 31, E, tid); }
;         { pg8::Gemm g{HID, WDN, MP, DM, DFF, DFF, DFF}; pg8::StaticOrder S; S.init(MP, DM, G, bx);
;           pg8::EpiResidB<1> E{nullptr, nullptr, X1B, Y, SSF}; pg8::gemm_phase<pg8::EpiResidB<1>, pg8::StaticOrder>(ldsl, g, S, E); }
.LBB0_994:
	s_cmp_lt_i32 s90, 8
	s_cselect_b64 s[4:5], -1, 0
	s_and_b64 s[0:1], s[4:5], s[0:1]
	s_andn2_b64 vcc, exec, s[0:1]
	s_cbranch_vccnz .LBB0_1051
	s_add_u32 s14, s86, 0x33400000
	s_addc_u32 s15, s87, 0
	s_bfe_u32 s100, s2, 0x10003
	s_cmpk_lt_i32 s2, 0x100
	v_lshrrev_b32_e32 v79, 2, v188
	s_cbranch_scc1 .Lp7_has_small
	v_lshrrev_b32_e32 v2, 3, v188
	v_lshlrev_b32_e32 v0, 4, v188
	s_waitcnt lgkmcnt(0)
	v_lshrrev_b32_e32 v1, 2, v188
	v_lshrrev_b32_e32 v3, 5, v188
	v_and_b32_e32 v78, 0x70, v2
	v_and_b32_e32 v8, 15, v188
	s_cbranch_execz .LBB0_998
	s_branch .LBB0_1009
.Lp7_has_small:
	s_cmp_eq_u32 s100, 1
	s_cbranch_scc0 .LBB0_997
	v_mov_b32_e32 v254, v188
	v_mov_b32_e32 v255, v189
	v_lshrrev_b32_e32 v2, 3, v188
	v_lshlrev_b32_e32 v0, 4, v188
	s_waitcnt lgkmcnt(0)
	v_lshrrev_b32_e32 v1, 2, v188
	v_lshrrev_b32_e32 v3, 5, v188
	v_and_b32_e32 v78, 0x70, v2
	v_and_b32_e32 v8, 15, v188
	s_branch .LBB0_1009

; __global__ void __launch_bounds__(512, 2) hybrid_fwd(Args a) {
;     ...
;         for (int t = bx; t < 256; t += G) { SmResidB<1> E{nullptr, X1B, Y, SSF}; small_gemm_tile<SmResidB<1>>(lds, HID, DFF, WDN, DFF, DFF, -1, MP, t >> 5, t & 31, E, tid); }
;         { pg8::Gemm g{HID, WDN, MP, DM, DFF, DFF, DFF}; pg8::StaticOrder S; S.init(MP, DM, G, bx);
;           pg8::EpiResidB<1> E{nullptr, nullptr, X1B, Y, SSF}; pg8::gemm_phase<pg8::EpiResidB<1>, pg8::StaticOrder>(ldsl, g, S, E); }
.LBB0_1008:
	s_cmp_eq_u32 s100, 2
	s_cbranch_scc1 .Lp7y_done
	v_mov_b32_e32 v0, v223
	v_mov_b32_e32 v1, v79
	v_mov_b32_e32 v3, v189
	v_mov_b32_e32 v2, v222
	v_mov_b32_e32 v8, v187

; #define PG8_WAIT_V(n) asm volatile("s_waitcnt vmcnt(" #n ")" ::: "memory")
; #define PG8_BAR __builtin_amdgcn_s_barrier()
; template <class Epi, class Sched>
; __device__ __forceinline__ void gemm_phase(LAS unsigned char* lds, const Gemm g, const Sched& S, const Epi& E) {
;     ...
;     PG8_WAIT_V(0);
;     PG8_BAR;
; __global__ void __launch_bounds__(512, 2) hybrid_fwd(Args a) {
;     ...
;         for (int t = bx; t < 256; t += G) { SmResidB<1> E{nullptr, X1B, Y, SSF}; small_gemm_tile<SmResidB<1>>(lds, HID, DFF, WDN, DFF, DFF, -1, MP, t >> 5, t & 31, E, tid); }
;         { pg8::Gemm g{HID, WDN, MP, DM, DFF, DFF, DFF}; pg8::StaticOrder S; S.init(MP, DM, G, bx);
;           pg8::EpiResidB<1> E{nullptr, nullptr, X1B, Y, SSF}; pg8::gemm_phase<pg8::EpiResidB<1>, pg8::StaticOrder>(ldsl, g, S, E); }
.LBB0_1050:
	s_waitcnt vmcnt(0)
	s_barrier
	s_cmp_eq_u32 s100, 1
	s_cbranch_scc0 .LBB0_1051
	s_mov_b32 s100, 2
	v_mov_b32_e32 v188, v254
	v_mov_b32_e32 v189, v255
	v_lshrrev_b32_e32 v79, 2, v188
	v_lshlrev_b32_e32 v223, 4, v188
	v_lshrrev_b32_e32 v222, 3, v188
	v_and_b32_e32 v187, 15, v188
	s_add_u32 s14, s86, 0x33400000
	s_addc_u32 s15, s87, 0
	s_branch .LBB0_998
